# HGRN state update: all eight KDT tile reads issued up front with only lanes q<2 active (v58 + kmask)
# baseline (speedup 1.0000x reference)
.LBB0_950:
	v_lshlrev_b32_e32 v0, 1, v135
	v_lshlrev_b32_e32 v1, 1, v154
	v_add3_u32 v2, s62, v0, v1
	v_add_u32_e32 v207, s62, v63
	v_lshl_add_u32 v227, v54, 1, v207
	v_add_u32_e32 v0, v2, v176
	ds_read_b128 v[36:39], v2 offset:4352
	ds_read_b128 v[40:43], v2
	ds_read_b128 v[208:211], v2 offset:4416
	ds_read_b128 v[184:187], v2 offset:64
	ds_read_b128 v[212:215], v2 offset:4480
	ds_read_b128 v[228:231], v2 offset:128
	ds_read_b128 v[232:235], v2 offset:4544
	ds_read_b128 v[236:239], v2 offset:192
	ds_read_b64 v[188:189], v227 offset:14848
	ds_read2_b64 v[240:243], v0 offset1:4
	ds_read2_b64 v[244:247], v0 offset0:8 offset1:12
	s_and_b64 s[12:13], s[54:55], s[52:53]
	v_mov_b32_e32 v190, v3
	v_mov_b32_e32 v191, v3
	s_waitcnt lgkmcnt(9)
	v_mfma_f32_16x16x32_bf16 v[36:39], v[36:39], v[40:43], 0
	s_waitcnt lgkmcnt(7)
	v_mfma_f32_16x16x32_bf16 v[36:39], v[208:211], v[184:187], v[36:39]
	s_waitcnt lgkmcnt(5)
	v_mfma_f32_16x16x32_bf16 v[36:39], v[212:215], v[228:231], v[36:39]
	s_waitcnt lgkmcnt(3)
	v_mfma_f32_16x16x32_bf16 v[36:39], v[232:235], v[236:239], v[36:39]
	ds_read2_b64 v[208:211], v0 offset0:16 offset1:20
	ds_read2_b64 v[212:215], v0 offset0:24 offset1:28
	v_cvt_pk_bf16_f32 v184, v4, v5
	v_cvt_pk_bf16_f32 v185, v6, v7
	v_cvt_pk_bf16_f32 v186, v8, v9
	v_cvt_pk_bf16_f32 v187, v10, v11
	v_mov_b32_e32 v2, v3
	s_nop 0
	v_cndmask_b32_e64 v192, v38, 0, s[12:13]
	s_and_b64 s[12:13], s[12:13], s[50:51]
	v_cndmask_b32_e64 v0, v37, 0, s[12:13]
	s_and_b64 s[12:13], s[12:13], s[48:49]
	v_cndmask_b32_e64 v36, v36, 0, s[12:13]
	v_cndmask_b32_e64 v1, v39, 0, s[54:55]
	v_cvt_pk_bf16_f32 v0, v36, v0
	v_cvt_pk_bf16_f32 v1, v192, v1
	s_nop 0
	s_waitcnt lgkmcnt(4)
	v_mfma_f32_16x16x32_bf16 v[36:39], v[188:191], v[0:3], 0
	v_cvt_pk_bf16_f32 v40, v12, v13
	v_cvt_pk_bf16_f32 v41, v14, v15
	v_cvt_pk_bf16_f32 v42, v16, v17
	v_cvt_pk_bf16_f32 v43, v18, v19
	v_cvt_pk_bf16_f32 v228, v20, v21
	v_cvt_pk_bf16_f32 v229, v22, v23
	v_cvt_pk_bf16_f32 v230, v24, v25
	v_cvt_pk_bf16_f32 v231, v26, v27
	v_cvt_pk_bf16_f32 v232, v28, v29
	v_cvt_pk_bf16_f32 v233, v30, v31
	v_cvt_pk_bf16_f32 v234, v32, v33
	v_cvt_pk_bf16_f32 v235, v34, v35
	s_waitcnt lgkmcnt(3)
	v_mfma_f32_16x16x32_bf16 v[36:39], v[184:187], v[240:243], v[36:39]
	s_waitcnt lgkmcnt(2)
	v_mfma_f32_16x16x32_bf16 v[36:39], v[40:43], v[244:247], v[36:39]
	s_waitcnt lgkmcnt(1)
	v_mfma_f32_16x16x32_bf16 v[36:39], v[228:231], v[208:211], v[36:39]
	s_waitcnt lgkmcnt(0)
	v_mfma_f32_16x16x32_bf16 v[36:39], v[232:235], v[212:215], v[36:39]
	v_add_u32_e32 v227, v207, v155
	v_add_u32_e32 v216, s62, v142
	v_add3_u32 v217, s62, v155, v156
	v_mov_b32_e32 v32, 0
	v_mov_b32_e32 v33, 0
	v_mov_b32_e32 v34, 0
	v_mov_b32_e32 v35, 0
	ds_read_b64 v[190:191], v216 offset:20992
	s_and_saveexec_b64 s[12:13], s[46:47]
	ds_read_b128 v[32:35], v227 offset:14848
	ds_read_b128 v[184:187], v217 offset:8704
	ds_read_b128 v[40:43], v217 offset:9472
	ds_read_b128 v[228:231], v217 offset:10240
	ds_read_b128 v[232:235], v217 offset:11008
	ds_read_b128 v[240:243], v217 offset:11776
	ds_read_b128 v[244:247], v217 offset:12544
	ds_read_b128 v[208:211], v217 offset:13312
	ds_read_b128 v[212:215], v217 offset:14080
	s_or_b64 exec, exec, s[12:13]
	s_ashr_i32 s12, s32, 4
	s_add_i32 s12, s12, -2
	v_sub_u32_e32 v0, v51, v54
	v_cvt_pk_bf16_f32 v192, v36, v37
	v_cvt_pk_bf16_f32 v193, v38, v39
	v_mad_i32_i24 v0, v0, s12, v197
	global_store_dwordx2 v0, v[192:193], s[100:101]
	s_waitcnt lgkmcnt(7)
	v_mul_f32_dpp v4, v190, v4 row_newbcast:0 row_mask:0xf bank_mask:0xf
	v_mul_f32_dpp v5, v191, v5 row_newbcast:0 row_mask:0xf bank_mask:0xf
	v_mul_f32_dpp v6, v190, v6 row_newbcast:1 row_mask:0xf bank_mask:0xf
	v_mul_f32_dpp v7, v191, v7 row_newbcast:1 row_mask:0xf bank_mask:0xf
	s_nop 1
	v_mfma_f32_16x16x32_bf16 v[4:7], v[184:187], v[32:35], v[4:7]
	s_waitcnt lgkmcnt(6)
	v_mul_f32_dpp v8, v190, v8 row_newbcast:2 row_mask:0xf bank_mask:0xf
	v_mul_f32_dpp v9, v191, v9 row_newbcast:2 row_mask:0xf bank_mask:0xf
	v_mul_f32_dpp v10, v190, v10 row_newbcast:3 row_mask:0xf bank_mask:0xf
	v_mul_f32_dpp v11, v191, v11 row_newbcast:3 row_mask:0xf bank_mask:0xf
	s_nop 1
	v_mfma_f32_16x16x32_bf16 v[8:11], v[40:43], v[32:35], v[8:11]
	s_waitcnt lgkmcnt(5)
	v_mul_f32_dpp v12, v190, v12 row_newbcast:4 row_mask:0xf bank_mask:0xf
	v_mul_f32_dpp v13, v191, v13 row_newbcast:4 row_mask:0xf bank_mask:0xf
	v_mul_f32_dpp v14, v190, v14 row_newbcast:5 row_mask:0xf bank_mask:0xf
	v_mul_f32_dpp v15, v191, v15 row_newbcast:5 row_mask:0xf bank_mask:0xf
	s_nop 1
	v_mfma_f32_16x16x32_bf16 v[12:15], v[228:231], v[32:35], v[12:15]
	s_waitcnt lgkmcnt(4)
	v_mul_f32_dpp v16, v190, v16 row_newbcast:6 row_mask:0xf bank_mask:0xf
	v_mul_f32_dpp v17, v191, v17 row_newbcast:6 row_mask:0xf bank_mask:0xf
	v_mul_f32_dpp v18, v190, v18 row_newbcast:7 row_mask:0xf bank_mask:0xf
	v_mul_f32_dpp v19, v191, v19 row_newbcast:7 row_mask:0xf bank_mask:0xf
	s_nop 1
	v_mfma_f32_16x16x32_bf16 v[16:19], v[232:235], v[32:35], v[16:19]
	s_waitcnt lgkmcnt(3)
	v_mul_f32_dpp v20, v190, v20 row_newbcast:8 row_mask:0xf bank_mask:0xf
	v_mul_f32_dpp v21, v191, v21 row_newbcast:8 row_mask:0xf bank_mask:0xf
	v_mul_f32_dpp v22, v190, v22 row_newbcast:9 row_mask:0xf bank_mask:0xf
	v_mul_f32_dpp v23, v191, v23 row_newbcast:9 row_mask:0xf bank_mask:0xf
	s_nop 1
	v_mfma_f32_16x16x32_bf16 v[20:23], v[240:243], v[32:35], v[20:23]
	s_waitcnt lgkmcnt(2)
	v_mul_f32_dpp v24, v190, v24 row_newbcast:10 row_mask:0xf bank_mask:0xf
	v_mul_f32_dpp v25, v191, v25 row_newbcast:10 row_mask:0xf bank_mask:0xf
	v_mul_f32_dpp v26, v190, v26 row_newbcast:11 row_mask:0xf bank_mask:0xf
	v_mul_f32_dpp v27, v191, v27 row_newbcast:11 row_mask:0xf bank_mask:0xf
	s_nop 1
	v_mfma_f32_16x16x32_bf16 v[24:27], v[244:247], v[32:35], v[24:27]
	s_waitcnt lgkmcnt(1)
	v_mul_f32_dpp v28, v190, v28 row_newbcast:12 row_mask:0xf bank_mask:0xf
	v_mul_f32_dpp v29, v191, v29 row_newbcast:12 row_mask:0xf bank_mask:0xf
	v_mul_f32_dpp v30, v190, v30 row_newbcast:13 row_mask:0xf bank_mask:0xf
	v_mul_f32_dpp v31, v191, v31 row_newbcast:13 row_mask:0xf bank_mask:0xf
	s_nop 1
	v_mfma_f32_16x16x32_bf16 v[28:31], v[208:211], v[32:35], v[28:31]
	s_waitcnt lgkmcnt(0)
	v_mul_f32_dpp v36, v190, v148 row_newbcast:14 row_mask:0xf bank_mask:0xf
	v_mul_f32_dpp v37, v191, v149 row_newbcast:14 row_mask:0xf bank_mask:0xf
	v_mul_f32_dpp v38, v190, v150 row_newbcast:15 row_mask:0xf bank_mask:0xf
	v_mul_f32_dpp v39, v191, v151 row_newbcast:15 row_mask:0xf bank_mask:0xf
	s_nop 1
	v_mfma_f32_16x16x32_bf16 v[32:35], v[212:215], v[32:35], v[36:39]
	v_add_u32_e32 v197, s32, v197
	v_add_u32_e32 v198, s32, v198
	v_add_u32_e32 v248, s32, v248
	v_add_u32_e32 v249, s32, v249
	v_lshl_add_u64 v[48:49], v[48:49], 0, v[46:47]
	s_add_i32 s60, s60, 16
	s_add_i32 s61, s61, 1
	s_cmpk_lg_i32 s60, 0x100
	s_barrier
	s_cbranch_scc1 .LBB0_943
	s_mov_b64 s[58:59], -1
	s_branch .LBB0_1005
.Lhc_alt_top:
	s_nop 2
	v_mov_b32_e32 v148, v32
	v_mov_b32_e32 v149, v33
	v_mov_b32_e32 v150, v34
	v_mov_b32_e32 v151, v35
	s_bitcmp1_b32 s61, 0
	s_cselect_b32 s62, 0x5800, 0
	v_lshlrev_b32_e32 v0, 1, v135
	v_lshlrev_b32_e32 v1, 1, v154
	v_add3_u32 v2, s62, v0, v1
	v_add_u32_e32 v207, s62, v63
	v_lshl_add_u32 v227, v54, 1, v207
	v_add_u32_e32 v0, v2, v176
	ds_read_b128 v[36:39], v2 offset:4352
	ds_read_b128 v[40:43], v2
	ds_read_b128 v[208:211], v2 offset:4416
	ds_read_b128 v[184:187], v2 offset:64
	ds_read_b128 v[212:215], v2 offset:4480
	ds_read_b128 v[228:231], v2 offset:128
	ds_read_b128 v[232:235], v2 offset:4544
	ds_read_b128 v[236:239], v2 offset:192
	ds_read_b64 v[188:189], v227 offset:14848
	ds_read2_b64 v[240:243], v0 offset1:4
	ds_read2_b64 v[244:247], v0 offset0:8 offset1:12
	s_and_b64 s[12:13], s[54:55], s[52:53]
	v_mov_b32_e32 v190, v3
	v_mov_b32_e32 v191, v3
	s_waitcnt lgkmcnt(9)
	v_mfma_f32_16x16x32_bf16 v[36:39], v[36:39], v[40:43], 0
	s_waitcnt lgkmcnt(7)
	v_mfma_f32_16x16x32_bf16 v[36:39], v[208:211], v[184:187], v[36:39]
	s_waitcnt lgkmcnt(5)
	v_mfma_f32_16x16x32_bf16 v[36:39], v[212:215], v[228:231], v[36:39]
	s_waitcnt lgkmcnt(3)
	v_mfma_f32_16x16x32_bf16 v[36:39], v[232:235], v[236:239], v[36:39]
	ds_read2_b64 v[208:211], v0 offset0:16 offset1:20
	ds_read2_b64 v[212:215], v0 offset0:24 offset1:28
	v_cvt_pk_bf16_f32 v184, v4, v5
	v_cvt_pk_bf16_f32 v185, v6, v7
	v_cvt_pk_bf16_f32 v186, v8, v9
	v_cvt_pk_bf16_f32 v187, v10, v11
	v_mov_b32_e32 v2, v3
	s_nop 0
	v_cndmask_b32_e64 v192, v38, 0, s[12:13]
	s_and_b64 s[12:13], s[12:13], s[50:51]
	v_cndmask_b32_e64 v0, v37, 0, s[12:13]
	s_and_b64 s[12:13], s[12:13], s[48:49]
	v_cndmask_b32_e64 v36, v36, 0, s[12:13]
	v_cndmask_b32_e64 v1, v39, 0, s[54:55]
	v_cvt_pk_bf16_f32 v0, v36, v0
	v_cvt_pk_bf16_f32 v1, v192, v1
	s_nop 0
	s_waitcnt lgkmcnt(4)
	v_mfma_f32_16x16x32_bf16 v[36:39], v[188:191], v[0:3], 0
	v_cvt_pk_bf16_f32 v40, v12, v13
	v_cvt_pk_bf16_f32 v41, v14, v15
	v_cvt_pk_bf16_f32 v42, v16, v17
	v_cvt_pk_bf16_f32 v43, v18, v19
	v_cvt_pk_bf16_f32 v228, v20, v21
	v_cvt_pk_bf16_f32 v229, v22, v23
	v_cvt_pk_bf16_f32 v230, v24, v25
	v_cvt_pk_bf16_f32 v231, v26, v27
	v_cvt_pk_bf16_f32 v232, v28, v29
	v_cvt_pk_bf16_f32 v233, v30, v31
	v_cvt_pk_bf16_f32 v234, v32, v33
	v_cvt_pk_bf16_f32 v235, v34, v35
	s_waitcnt lgkmcnt(3)
	v_mfma_f32_16x16x32_bf16 v[36:39], v[184:187], v[240:243], v[36:39]
	s_waitcnt lgkmcnt(2)
	v_mfma_f32_16x16x32_bf16 v[36:39], v[40:43], v[244:247], v[36:39]
	s_waitcnt lgkmcnt(1)
	v_mfma_f32_16x16x32_bf16 v[36:39], v[228:231], v[208:211], v[36:39]
	s_waitcnt lgkmcnt(0)
	v_mfma_f32_16x16x32_bf16 v[36:39], v[232:235], v[212:215], v[36:39]
	v_add_u32_e32 v227, v207, v155
	v_add_u32_e32 v216, s62, v142
	v_add3_u32 v217, s62, v155, v156
	v_mov_b32_e32 v32, 0
	v_mov_b32_e32 v33, 0
	v_mov_b32_e32 v34, 0
	v_mov_b32_e32 v35, 0
	ds_read_b64 v[190:191], v216 offset:20992
	s_and_saveexec_b64 s[12:13], s[46:47]
	ds_read_b128 v[32:35], v227 offset:14848
	ds_read_b128 v[184:187], v217 offset:8704
	ds_read_b128 v[40:43], v217 offset:9472
	ds_read_b128 v[228:231], v217 offset:10240
	ds_read_b128 v[232:235], v217 offset:11008
	ds_read_b128 v[240:243], v217 offset:11776
	ds_read_b128 v[244:247], v217 offset:12544
	ds_read_b128 v[208:211], v217 offset:13312
	ds_read_b128 v[212:215], v217 offset:14080
	s_or_b64 exec, exec, s[12:13]
	s_ashr_i32 s12, s32, 4
	s_add_i32 s12, s12, -2
	v_sub_u32_e32 v0, v51, v54
	v_cvt_pk_bf16_f32 v192, v36, v37
	v_cvt_pk_bf16_f32 v193, v38, v39
	v_mad_i32_i24 v0, v0, s12, v197
	global_store_dwordx2 v0, v[192:193], s[100:101]
	s_waitcnt lgkmcnt(7)
	v_mul_f32_dpp v4, v190, v4 row_newbcast:0 row_mask:0xf bank_mask:0xf
	v_mul_f32_dpp v5, v191, v5 row_newbcast:0 row_mask:0xf bank_mask:0xf
	v_mul_f32_dpp v6, v190, v6 row_newbcast:1 row_mask:0xf bank_mask:0xf
	v_mul_f32_dpp v7, v191, v7 row_newbcast:1 row_mask:0xf bank_mask:0xf
	s_nop 1
	v_mfma_f32_16x16x32_bf16 v[4:7], v[184:187], v[32:35], v[4:7]
	s_waitcnt lgkmcnt(6)
	v_mul_f32_dpp v8, v190, v8 row_newbcast:2 row_mask:0xf bank_mask:0xf
	v_mul_f32_dpp v9, v191, v9 row_newbcast:2 row_mask:0xf bank_mask:0xf
	v_mul_f32_dpp v10, v190, v10 row_newbcast:3 row_mask:0xf bank_mask:0xf
	v_mul_f32_dpp v11, v191, v11 row_newbcast:3 row_mask:0xf bank_mask:0xf
	s_nop 1
	v_mfma_f32_16x16x32_bf16 v[8:11], v[40:43], v[32:35], v[8:11]
	s_waitcnt lgkmcnt(5)
	v_mul_f32_dpp v12, v190, v12 row_newbcast:4 row_mask:0xf bank_mask:0xf
	v_mul_f32_dpp v13, v191, v13 row_newbcast:4 row_mask:0xf bank_mask:0xf
	v_mul_f32_dpp v14, v190, v14 row_newbcast:5 row_mask:0xf bank_mask:0xf
	v_mul_f32_dpp v15, v191, v15 row_newbcast:5 row_mask:0xf bank_mask:0xf
	s_nop 1
	v_mfma_f32_16x16x32_bf16 v[12:15], v[228:231], v[32:35], v[12:15]
	s_waitcnt lgkmcnt(4)
	v_mul_f32_dpp v16, v190, v16 row_newbcast:6 row_mask:0xf bank_mask:0xf
	v_mul_f32_dpp v17, v191, v17 row_newbcast:6 row_mask:0xf bank_mask:0xf
	v_mul_f32_dpp v18, v190, v18 row_newbcast:7 row_mask:0xf bank_mask:0xf
	v_mul_f32_dpp v19, v191, v19 row_newbcast:7 row_mask:0xf bank_mask:0xf
	s_nop 1
	v_mfma_f32_16x16x32_bf16 v[16:19], v[232:235], v[32:35], v[16:19]
	s_waitcnt lgkmcnt(3)
	v_mul_f32_dpp v20, v190, v20 row_newbcast:8 row_mask:0xf bank_mask:0xf
	v_mul_f32_dpp v21, v191, v21 row_newbcast:8 row_mask:0xf bank_mask:0xf
	v_mul_f32_dpp v22, v190, v22 row_newbcast:9 row_mask:0xf bank_mask:0xf
	v_mul_f32_dpp v23, v191, v23 row_newbcast:9 row_mask:0xf bank_mask:0xf
	s_nop 1
	v_mfma_f32_16x16x32_bf16 v[20:23], v[240:243], v[32:35], v[20:23]
	s_waitcnt lgkmcnt(2)
	v_mul_f32_dpp v24, v190, v24 row_newbcast:10 row_mask:0xf bank_mask:0xf
	v_mul_f32_dpp v25, v191, v25 row_newbcast:10 row_mask:0xf bank_mask:0xf
	v_mul_f32_dpp v26, v190, v26 row_newbcast:11 row_mask:0xf bank_mask:0xf
	v_mul_f32_dpp v27, v191, v27 row_newbcast:11 row_mask:0xf bank_mask:0xf
	s_nop 1
	v_mfma_f32_16x16x32_bf16 v[24:27], v[244:247], v[32:35], v[24:27]
	s_waitcnt lgkmcnt(1)
	v_mul_f32_dpp v28, v190, v28 row_newbcast:12 row_mask:0xf bank_mask:0xf
	v_mul_f32_dpp v29, v191, v29 row_newbcast:12 row_mask:0xf bank_mask:0xf
	v_mul_f32_dpp v30, v190, v30 row_newbcast:13 row_mask:0xf bank_mask:0xf
	v_mul_f32_dpp v31, v191, v31 row_newbcast:13 row_mask:0xf bank_mask:0xf
	s_nop 1
	v_mfma_f32_16x16x32_bf16 v[28:31], v[208:211], v[32:35], v[28:31]
	s_waitcnt lgkmcnt(0)
	v_mul_f32_dpp v36, v190, v148 row_newbcast:14 row_mask:0xf bank_mask:0xf
	v_mul_f32_dpp v37, v191, v149 row_newbcast:14 row_mask:0xf bank_mask:0xf
	v_mul_f32_dpp v38, v190, v150 row_newbcast:15 row_mask:0xf bank_mask:0xf
	v_mul_f32_dpp v39, v191, v151 row_newbcast:15 row_mask:0xf bank_mask:0xf
	s_nop 1
	v_mfma_f32_16x16x32_bf16 v[32:35], v[212:215], v[32:35], v[36:39]
	s_cmp_gt_u32 s61, 14
	s_cbranch_scc1 .Lhc_alt_tail
	s_waitcnt vmcnt(1)
	v_mov_b32_e32 v44, v200
	v_mov_b32_e32 v42, v202
	v_mov_b32_e32 v40, v204
	v_mov_b32_e32 v38, v206
	v_mov_b32_e32 v45, v199
	v_mov_b32_e32 v43, v201
	v_mov_b32_e32 v41, v203
	v_mov_b32_e32 v39, v205
	v_mov_b64_e32 v[36:37], v[152:153]
	s_cmpk_eq_i32 s60, 0xe0
	s_cbranch_scc1 .Lhc_alt_947
	global_load_ushort v199, v197, s[24:25]
	global_load_ushort v200, v197, s[98:99]
	global_load_ushort v201, v198, s[24:25]
	global_load_ushort v202, v198, s[98:99]
	global_load_ushort v203, v248, s[24:25]
	global_load_ushort v204, v248, s[98:99]
	global_load_ushort v205, v249, s[24:25]
	global_load_ushort v206, v249, s[98:99]
	global_load_dwordx2 v[152:153], v[48:49], off

.LBB0_985:
	v_lshlrev_b32_e32 v0, 1, v135
	v_lshlrev_b32_e32 v1, 1, v154
	v_add3_u32 v2, s82, v0, v1
	v_add_u32_e32 v207, s82, v63
	v_lshl_add_u32 v227, v54, 1, v207
	v_add_u32_e32 v0, v2, v176
	ds_read_b128 v[36:39], v2 offset:4352
	ds_read_b128 v[40:43], v2
	ds_read_b128 v[208:211], v2 offset:4416
	ds_read_b128 v[184:187], v2 offset:64
	ds_read_b128 v[212:215], v2 offset:4480
	ds_read_b128 v[228:231], v2 offset:128
	ds_read_b128 v[232:235], v2 offset:4544
	ds_read_b128 v[236:239], v2 offset:192
	ds_read_b64 v[188:189], v227 offset:14848
	ds_read2_b64 v[240:243], v0 offset1:4
	ds_read2_b64 v[244:247], v0 offset0:8 offset1:12
	s_and_b64 s[14:15], s[54:55], s[52:53]
	v_mov_b32_e32 v190, v3
	v_mov_b32_e32 v191, v3
	s_waitcnt lgkmcnt(9)
	v_mfma_f32_16x16x32_bf16 v[36:39], v[36:39], v[40:43], 0
	s_waitcnt lgkmcnt(7)
	v_mfma_f32_16x16x32_bf16 v[36:39], v[208:211], v[184:187], v[36:39]
	s_waitcnt lgkmcnt(5)
	v_mfma_f32_16x16x32_bf16 v[36:39], v[212:215], v[228:231], v[36:39]
	s_waitcnt lgkmcnt(3)
	v_mfma_f32_16x16x32_bf16 v[36:39], v[232:235], v[236:239], v[36:39]
	ds_read2_b64 v[208:211], v0 offset0:16 offset1:20
	ds_read2_b64 v[212:215], v0 offset0:24 offset1:28
	v_cvt_pk_bf16_f32 v184, v4, v5
	v_cvt_pk_bf16_f32 v185, v6, v7
	v_cvt_pk_bf16_f32 v186, v8, v9
	v_cvt_pk_bf16_f32 v187, v10, v11
	v_mov_b32_e32 v2, v3
	s_nop 0
	v_cndmask_b32_e64 v192, v38, 0, s[14:15]
	s_and_b64 s[14:15], s[14:15], s[50:51]
	v_cndmask_b32_e64 v0, v37, 0, s[14:15]
	s_and_b64 s[14:15], s[14:15], s[48:49]
	v_cndmask_b32_e64 v36, v36, 0, s[14:15]
	v_cndmask_b32_e64 v1, v39, 0, s[54:55]
	v_cvt_pk_bf16_f32 v0, v36, v0
	v_cvt_pk_bf16_f32 v1, v192, v1
	s_nop 0
	s_waitcnt lgkmcnt(4)
	v_mfma_f32_16x16x32_bf16 v[36:39], v[188:191], v[0:3], 0
	v_cvt_pk_bf16_f32 v40, v12, v13
	v_cvt_pk_bf16_f32 v41, v14, v15
	v_cvt_pk_bf16_f32 v42, v16, v17
	v_cvt_pk_bf16_f32 v43, v18, v19
	v_cvt_pk_bf16_f32 v228, v20, v21
	v_cvt_pk_bf16_f32 v229, v22, v23
	v_cvt_pk_bf16_f32 v230, v24, v25
	v_cvt_pk_bf16_f32 v231, v26, v27
	v_cvt_pk_bf16_f32 v232, v28, v29
	v_cvt_pk_bf16_f32 v233, v30, v31
	v_cvt_pk_bf16_f32 v234, v32, v33
	v_cvt_pk_bf16_f32 v235, v34, v35
	s_waitcnt lgkmcnt(3)
	v_mfma_f32_16x16x32_bf16 v[36:39], v[184:187], v[240:243], v[36:39]
	s_waitcnt lgkmcnt(2)
	v_mfma_f32_16x16x32_bf16 v[36:39], v[40:43], v[244:247], v[36:39]
	s_waitcnt lgkmcnt(1)
	v_mfma_f32_16x16x32_bf16 v[36:39], v[228:231], v[208:211], v[36:39]
	s_waitcnt lgkmcnt(0)
	v_mfma_f32_16x16x32_bf16 v[36:39], v[232:235], v[212:215], v[36:39]
	v_add_u32_e32 v227, v207, v155
	v_add_u32_e32 v216, s82, v142
	v_add3_u32 v217, s82, v155, v156
	v_mov_b32_e32 v44, 0
	v_mov_b32_e32 v45, 0
	v_mov_b32_e32 v46, 0
	v_mov_b32_e32 v47, 0
	ds_read_b64 v[190:191], v216 offset:20992
	s_and_saveexec_b64 s[14:15], s[46:47]
	ds_read_b128 v[44:47], v227 offset:14848
	ds_read_b128 v[184:187], v217 offset:8704
	ds_read_b128 v[40:43], v217 offset:9472
	ds_read_b128 v[228:231], v217 offset:10240
	ds_read_b128 v[232:235], v217 offset:11008
	ds_read_b128 v[240:243], v217 offset:11776
	ds_read_b128 v[244:247], v217 offset:12544
	ds_read_b128 v[208:211], v217 offset:13312
	ds_read_b128 v[212:215], v217 offset:14080
	s_or_b64 exec, exec, s[14:15]
	s_ashr_i32 s14, s32, 4
	s_add_i32 s14, s14, -2
	v_sub_u32_e32 v0, v51, v54
	v_cvt_pk_bf16_f32 v192, v36, v37
	v_cvt_pk_bf16_f32 v193, v38, v39
	v_mad_i32_i24 v0, v0, s14, v197
	global_store_dwordx2 v0, v[192:193], s[100:101]
	s_waitcnt lgkmcnt(7)
	v_mul_f32_dpp v4, v190, v4 row_newbcast:0 row_mask:0xf bank_mask:0xf
	v_mul_f32_dpp v5, v191, v5 row_newbcast:0 row_mask:0xf bank_mask:0xf
	v_mul_f32_dpp v6, v190, v6 row_newbcast:1 row_mask:0xf bank_mask:0xf
	v_mul_f32_dpp v7, v191, v7 row_newbcast:1 row_mask:0xf bank_mask:0xf
	s_nop 1
	v_mfma_f32_16x16x32_bf16 v[4:7], v[184:187], v[44:47], v[4:7]
	s_waitcnt lgkmcnt(6)
	v_mul_f32_dpp v8, v190, v8 row_newbcast:2 row_mask:0xf bank_mask:0xf
	v_mul_f32_dpp v9, v191, v9 row_newbcast:2 row_mask:0xf bank_mask:0xf
	v_mul_f32_dpp v10, v190, v10 row_newbcast:3 row_mask:0xf bank_mask:0xf
	v_mul_f32_dpp v11, v191, v11 row_newbcast:3 row_mask:0xf bank_mask:0xf
	s_nop 1
	v_mfma_f32_16x16x32_bf16 v[8:11], v[40:43], v[44:47], v[8:11]
	s_waitcnt lgkmcnt(5)
	v_mul_f32_dpp v12, v190, v12 row_newbcast:4 row_mask:0xf bank_mask:0xf
	v_mul_f32_dpp v13, v191, v13 row_newbcast:4 row_mask:0xf bank_mask:0xf
	v_mul_f32_dpp v14, v190, v14 row_newbcast:5 row_mask:0xf bank_mask:0xf
	v_mul_f32_dpp v15, v191, v15 row_newbcast:5 row_mask:0xf bank_mask:0xf
	s_nop 1
	v_mfma_f32_16x16x32_bf16 v[12:15], v[228:231], v[44:47], v[12:15]
	s_waitcnt lgkmcnt(4)
	v_mul_f32_dpp v16, v190, v16 row_newbcast:6 row_mask:0xf bank_mask:0xf
	v_mul_f32_dpp v17, v191, v17 row_newbcast:6 row_mask:0xf bank_mask:0xf
	v_mul_f32_dpp v18, v190, v18 row_newbcast:7 row_mask:0xf bank_mask:0xf
	v_mul_f32_dpp v19, v191, v19 row_newbcast:7 row_mask:0xf bank_mask:0xf
	s_nop 1
	v_mfma_f32_16x16x32_bf16 v[16:19], v[232:235], v[44:47], v[16:19]
	s_waitcnt lgkmcnt(3)
	v_mul_f32_dpp v20, v190, v20 row_newbcast:8 row_mask:0xf bank_mask:0xf
	v_mul_f32_dpp v21, v191, v21 row_newbcast:8 row_mask:0xf bank_mask:0xf
	v_mul_f32_dpp v22, v190, v22 row_newbcast:9 row_mask:0xf bank_mask:0xf
	v_mul_f32_dpp v23, v191, v23 row_newbcast:9 row_mask:0xf bank_mask:0xf
	s_nop 1
	v_mfma_f32_16x16x32_bf16 v[20:23], v[240:243], v[44:47], v[20:23]
	s_waitcnt lgkmcnt(2)
	v_mul_f32_dpp v24, v190, v24 row_newbcast:10 row_mask:0xf bank_mask:0xf
	v_mul_f32_dpp v25, v191, v25 row_newbcast:10 row_mask:0xf bank_mask:0xf
	v_mul_f32_dpp v26, v190, v26 row_newbcast:11 row_mask:0xf bank_mask:0xf
	v_mul_f32_dpp v27, v191, v27 row_newbcast:11 row_mask:0xf bank_mask:0xf
	s_nop 1
	v_mfma_f32_16x16x32_bf16 v[24:27], v[244:247], v[44:47], v[24:27]
	s_waitcnt lgkmcnt(1)
	v_mul_f32_dpp v28, v190, v28 row_newbcast:12 row_mask:0xf bank_mask:0xf
	v_mul_f32_dpp v29, v191, v29 row_newbcast:12 row_mask:0xf bank_mask:0xf
	v_mul_f32_dpp v30, v190, v30 row_newbcast:13 row_mask:0xf bank_mask:0xf
	v_mul_f32_dpp v31, v191, v31 row_newbcast:13 row_mask:0xf bank_mask:0xf
	s_nop 1
	v_mfma_f32_16x16x32_bf16 v[28:31], v[208:211], v[44:47], v[28:31]
	s_waitcnt lgkmcnt(0)
	v_mul_f32_dpp v32, v190, v32 row_newbcast:14 row_mask:0xf bank_mask:0xf
	v_mul_f32_dpp v33, v191, v33 row_newbcast:14 row_mask:0xf bank_mask:0xf
	v_mul_f32_dpp v34, v190, v34 row_newbcast:15 row_mask:0xf bank_mask:0xf
	v_mul_f32_dpp v35, v191, v35 row_newbcast:15 row_mask:0xf bank_mask:0xf
	s_nop 1
	v_mfma_f32_16x16x32_bf16 v[32:35], v[212:215], v[44:47], v[32:35]
	v_add_u32_e32 v197, s32, v197
	v_add_u32_e32 v198, s32, v198
	v_add_u32_e32 v178, s32, v178
	v_add_u32_e32 v179, s32, v179
	v_lshl_add_u64 v[150:151], v[150:151], 0, v[146:147]
	s_add_i32 s81, s81, 1
	s_add_i32 s62, s62, 16
	s_add_i32 s14, s80, s81
	s_cmp_eq_u32 s14, 2
	s_barrier
	s_cbranch_scc1 .LBB0_1003
	s_branch .LBB0_979
.Lhl_alt_top:
	s_bitcmp1_b32 s81, 0
	s_cselect_b32 s82, 0x5800, 0
	v_lshlrev_b32_e32 v0, 1, v135
	v_lshlrev_b32_e32 v1, 1, v154
	v_add3_u32 v2, s82, v0, v1
	v_add_u32_e32 v207, s82, v63
	v_lshl_add_u32 v227, v54, 1, v207
	v_add_u32_e32 v0, v2, v176
	ds_read_b128 v[36:39], v2 offset:4352
	ds_read_b128 v[40:43], v2
	ds_read_b128 v[208:211], v2 offset:4416
	ds_read_b128 v[184:187], v2 offset:64
	ds_read_b128 v[212:215], v2 offset:4480
	ds_read_b128 v[228:231], v2 offset:128
	ds_read_b128 v[232:235], v2 offset:4544
	ds_read_b128 v[236:239], v2 offset:192
	ds_read_b64 v[188:189], v227 offset:14848
	ds_read2_b64 v[240:243], v0 offset1:4
	ds_read2_b64 v[244:247], v0 offset0:8 offset1:12
	s_and_b64 s[14:15], s[54:55], s[52:53]
	v_mov_b32_e32 v190, v3
	v_mov_b32_e32 v191, v3
	s_waitcnt lgkmcnt(9)
	v_mfma_f32_16x16x32_bf16 v[36:39], v[36:39], v[40:43], 0
	s_waitcnt lgkmcnt(7)
	v_mfma_f32_16x16x32_bf16 v[36:39], v[208:211], v[184:187], v[36:39]
	s_waitcnt lgkmcnt(5)
	v_mfma_f32_16x16x32_bf16 v[36:39], v[212:215], v[228:231], v[36:39]
	s_waitcnt lgkmcnt(3)
	v_mfma_f32_16x16x32_bf16 v[36:39], v[232:235], v[236:239], v[36:39]
	ds_read2_b64 v[208:211], v0 offset0:16 offset1:20
	ds_read2_b64 v[212:215], v0 offset0:24 offset1:28
	v_cvt_pk_bf16_f32 v184, v4, v5
	v_cvt_pk_bf16_f32 v185, v6, v7
	v_cvt_pk_bf16_f32 v186, v8, v9
	v_cvt_pk_bf16_f32 v187, v10, v11
	v_mov_b32_e32 v2, v3
	s_nop 0
	v_cndmask_b32_e64 v192, v38, 0, s[14:15]
	s_and_b64 s[14:15], s[14:15], s[50:51]
	v_cndmask_b32_e64 v0, v37, 0, s[14:15]
	s_and_b64 s[14:15], s[14:15], s[48:49]
	v_cndmask_b32_e64 v36, v36, 0, s[14:15]
	v_cndmask_b32_e64 v1, v39, 0, s[54:55]
	v_cvt_pk_bf16_f32 v0, v36, v0
	v_cvt_pk_bf16_f32 v1, v192, v1
	s_nop 0
	s_waitcnt lgkmcnt(4)
	v_mfma_f32_16x16x32_bf16 v[36:39], v[188:191], v[0:3], 0
	v_cvt_pk_bf16_f32 v40, v12, v13
	v_cvt_pk_bf16_f32 v41, v14, v15
	v_cvt_pk_bf16_f32 v42, v16, v17
	v_cvt_pk_bf16_f32 v43, v18, v19
	v_cvt_pk_bf16_f32 v228, v20, v21
	v_cvt_pk_bf16_f32 v229, v22, v23
	v_cvt_pk_bf16_f32 v230, v24, v25
	v_cvt_pk_bf16_f32 v231, v26, v27
	v_cvt_pk_bf16_f32 v232, v28, v29
	v_cvt_pk_bf16_f32 v233, v30, v31
	v_cvt_pk_bf16_f32 v234, v32, v33
	v_cvt_pk_bf16_f32 v235, v34, v35
	s_waitcnt lgkmcnt(3)
	v_mfma_f32_16x16x32_bf16 v[36:39], v[184:187], v[240:243], v[36:39]
	s_waitcnt lgkmcnt(2)
	v_mfma_f32_16x16x32_bf16 v[36:39], v[40:43], v[244:247], v[36:39]
	s_waitcnt lgkmcnt(1)
	v_mfma_f32_16x16x32_bf16 v[36:39], v[228:231], v[208:211], v[36:39]
	s_waitcnt lgkmcnt(0)
	v_mfma_f32_16x16x32_bf16 v[36:39], v[232:235], v[212:215], v[36:39]
	v_add_u32_e32 v227, v207, v155
	v_add_u32_e32 v216, s82, v142
	v_add3_u32 v217, s82, v155, v156
	v_mov_b32_e32 v44, 0
	v_mov_b32_e32 v45, 0
	v_mov_b32_e32 v46, 0
	v_mov_b32_e32 v47, 0
	ds_read_b64 v[190:191], v216 offset:20992
	s_and_saveexec_b64 s[14:15], s[46:47]
	ds_read_b128 v[44:47], v227 offset:14848
	ds_read_b128 v[184:187], v217 offset:8704
	ds_read_b128 v[40:43], v217 offset:9472
	ds_read_b128 v[228:231], v217 offset:10240
	ds_read_b128 v[232:235], v217 offset:11008
	ds_read_b128 v[240:243], v217 offset:11776
	ds_read_b128 v[244:247], v217 offset:12544
	ds_read_b128 v[208:211], v217 offset:13312
	ds_read_b128 v[212:215], v217 offset:14080
	s_or_b64 exec, exec, s[14:15]
	s_ashr_i32 s14, s32, 4
	s_add_i32 s14, s14, -2
	v_sub_u32_e32 v0, v51, v54
	v_cvt_pk_bf16_f32 v192, v36, v37
	v_cvt_pk_bf16_f32 v193, v38, v39
	v_mad_i32_i24 v0, v0, s14, v197
	global_store_dwordx2 v0, v[192:193], s[100:101]
	s_waitcnt lgkmcnt(7)
	v_mul_f32_dpp v4, v190, v4 row_newbcast:0 row_mask:0xf bank_mask:0xf
	v_mul_f32_dpp v5, v191, v5 row_newbcast:0 row_mask:0xf bank_mask:0xf
	v_mul_f32_dpp v6, v190, v6 row_newbcast:1 row_mask:0xf bank_mask:0xf
	v_mul_f32_dpp v7, v191, v7 row_newbcast:1 row_mask:0xf bank_mask:0xf
	s_nop 1
	v_mfma_f32_16x16x32_bf16 v[4:7], v[184:187], v[44:47], v[4:7]
	s_waitcnt lgkmcnt(6)
	v_mul_f32_dpp v8, v190, v8 row_newbcast:2 row_mask:0xf bank_mask:0xf
	v_mul_f32_dpp v9, v191, v9 row_newbcast:2 row_mask:0xf bank_mask:0xf
	v_mul_f32_dpp v10, v190, v10 row_newbcast:3 row_mask:0xf bank_mask:0xf
	v_mul_f32_dpp v11, v191, v11 row_newbcast:3 row_mask:0xf bank_mask:0xf
	s_nop 1
	v_mfma_f32_16x16x32_bf16 v[8:11], v[40:43], v[44:47], v[8:11]
	s_waitcnt lgkmcnt(5)
	v_mul_f32_dpp v12, v190, v12 row_newbcast:4 row_mask:0xf bank_mask:0xf
	v_mul_f32_dpp v13, v191, v13 row_newbcast:4 row_mask:0xf bank_mask:0xf
	v_mul_f32_dpp v14, v190, v14 row_newbcast:5 row_mask:0xf bank_mask:0xf
	v_mul_f32_dpp v15, v191, v15 row_newbcast:5 row_mask:0xf bank_mask:0xf
	s_nop 1
	v_mfma_f32_16x16x32_bf16 v[12:15], v[228:231], v[44:47], v[12:15]
	s_waitcnt lgkmcnt(4)
	v_mul_f32_dpp v16, v190, v16 row_newbcast:6 row_mask:0xf bank_mask:0xf
	v_mul_f32_dpp v17, v191, v17 row_newbcast:6 row_mask:0xf bank_mask:0xf
	v_mul_f32_dpp v18, v190, v18 row_newbcast:7 row_mask:0xf bank_mask:0xf
	v_mul_f32_dpp v19, v191, v19 row_newbcast:7 row_mask:0xf bank_mask:0xf
	s_nop 1
	v_mfma_f32_16x16x32_bf16 v[16:19], v[232:235], v[44:47], v[16:19]
	s_waitcnt lgkmcnt(3)
	v_mul_f32_dpp v20, v190, v20 row_newbcast:8 row_mask:0xf bank_mask:0xf
	v_mul_f32_dpp v21, v191, v21 row_newbcast:8 row_mask:0xf bank_mask:0xf
	v_mul_f32_dpp v22, v190, v22 row_newbcast:9 row_mask:0xf bank_mask:0xf
	v_mul_f32_dpp v23, v191, v23 row_newbcast:9 row_mask:0xf bank_mask:0xf
	s_nop 1
	v_mfma_f32_16x16x32_bf16 v[20:23], v[240:243], v[44:47], v[20:23]
	s_waitcnt lgkmcnt(2)
	v_mul_f32_dpp v24, v190, v24 row_newbcast:10 row_mask:0xf bank_mask:0xf
	v_mul_f32_dpp v25, v191, v25 row_newbcast:10 row_mask:0xf bank_mask:0xf
	v_mul_f32_dpp v26, v190, v26 row_newbcast:11 row_mask:0xf bank_mask:0xf
	v_mul_f32_dpp v27, v191, v27 row_newbcast:11 row_mask:0xf bank_mask:0xf
	s_nop 1
	v_mfma_f32_16x16x32_bf16 v[24:27], v[244:247], v[44:47], v[24:27]
	s_waitcnt lgkmcnt(1)
	v_mul_f32_dpp v28, v190, v28 row_newbcast:12 row_mask:0xf bank_mask:0xf
	v_mul_f32_dpp v29, v191, v29 row_newbcast:12 row_mask:0xf bank_mask:0xf
	v_mul_f32_dpp v30, v190, v30 row_newbcast:13 row_mask:0xf bank_mask:0xf
	v_mul_f32_dpp v31, v191, v31 row_newbcast:13 row_mask:0xf bank_mask:0xf
	s_nop 1
	v_mfma_f32_16x16x32_bf16 v[28:31], v[208:211], v[44:47], v[28:31]
	s_waitcnt lgkmcnt(0)
	v_mul_f32_dpp v32, v190, v32 row_newbcast:14 row_mask:0xf bank_mask:0xf
	v_mul_f32_dpp v33, v191, v33 row_newbcast:14 row_mask:0xf bank_mask:0xf
	v_mul_f32_dpp v34, v190, v34 row_newbcast:15 row_mask:0xf bank_mask:0xf
	v_mul_f32_dpp v35, v191, v35 row_newbcast:15 row_mask:0xf bank_mask:0xf
	s_nop 1
	v_mfma_f32_16x16x32_bf16 v[32:35], v[212:215], v[44:47], v[32:35]
	s_add_i32 s14, s81, -1
	s_cmp_ge_u32 s14, s61
	s_cbranch_scc1 .Lhl_alt_tail
	s_cmp_ge_u32 s81, s61
	s_waitcnt vmcnt(1)
	v_mov_b32_e32 v199, v157
	v_mov_b32_e32 v200, v159
	v_mov_b32_e32 v201, v161
	v_mov_b32_e32 v202, v163
	v_mov_b32_e32 v203, v166
	v_mov_b32_e32 v204, v167
	v_mov_b32_e32 v205, v168
	v_mov_b32_e32 v206, v169
	v_mov_b64_e32 v[148:149], v[164:165]
	s_cbranch_scc1 .Lhl_alt_982
	global_load_ushort v168, v197, s[12:13]
	global_load_ushort v169, v197, s[98:99]
	global_load_ushort v166, v198, s[12:13]
	global_load_ushort v167, v198, s[98:99]
	global_load_ushort v161, v178, s[12:13]
	global_load_ushort v163, v178, s[98:99]
	global_load_ushort v157, v179, s[12:13]
	global_load_ushort v159, v179, s[98:99]
	global_load_dwordx2 v[164:165], v[150:151], off
